# v112 + GDN counted waits: top wait vmcnt(2) (next-chunk raw loads only), Minv/QK-table loads waited with vmcnt(4) just before use, output stores deferred after that wait
# baseline (speedup 1.0000x reference)
; __device__ __forceinline__ int otid() { int t = threadIdx.x; asm volatile("" : "+v"(t)); return t; }
; __device__ __forceinline__ void gdn_item(const Params& p, int item, float* sm) {
;   const int b = item >> 5, h = (item >> 3) & 3, c0 = (item & 7) * 16;
;   const bf16_t* gp = (const bf16_t*)p.out;
;   const float* gg = (const float*)(p.ws + OFF_GG);
;   bf16_t* O = (bf16_t*)(p.ws + OFF_O);
;   constexpr int TC = 16;
;   constexpr int BUF = 2 * TC * 128 + TC * 16 + 2 * TC + TC * 16 + TC;
;   const int tid = otid(), lane = tid & 63, wave = tid >> 6;
;   const int sub = lane & 15, cw = wave * 4 + (lane >> 4);
;   const int ltt = tid >> 4, lseg = tid & 15;
;   float S[8];
; #pragma unroll
;   for (int i = 0; i < 8; i++) S[i] = 0.f;
;   const size_t rowb = (size_t)b * LP;
;   uint4 pq, pk; bf16_t pv; float pg = 0.f, pb = 0.f;
;     ...
;   __syncthreads();
;   GDN_LOAD(PADR)
;   GDN_STORE(0)
;   __syncthreads();
.Lgd_item:
	s_setprio 3
	v_readlane_b32 s14, v244, 27
	v_readlane_b32 s8, v247, 3
	v_readlane_b32 s9, v247, 4
	v_readlane_b32 s4, v247, 1
	v_readlane_b32 s5, v247, 2
	v_and_b32_e32 v136, 15, v2
	v_lshrrev_b32_e32 v137, 4, v2
	v_bfe_u32 v138, v2, 4, 2
	v_lshrrev_b32_e32 v139, 6, v2
	s_lshr_b32 s10, s14, 5
	s_bfe_u32 s11, s14, 0x20003
	s_and_b32 s12, s14, 7
	s_lshl_b32 s12, s12, 5
	s_mul_i32 s13, s10, 0x2080
	s_add_i32 s13, s13, 0x70
	s_add_u32 s6, s8, 0x19c8c000
	s_addc_u32 s7, s9, 0
	s_add_u32 s8, s8, 0x19d90000
	s_addc_u32 s9, s9, 0
	s_lshl_b32 s14, s10, 2
	s_add_i32 s14, s14, s11
	s_mul_i32 s14, s14, 0x80400
	s_add_u32 s10, s4, 0x71a0000
	s_addc_u32 s15, s5, 0
	s_add_u32 s10, s10, s14
	s_addc_u32 s11, s15, 0
	v_readfirstlane_b32 s100, v139
	v_lshlrev_b32_e32 v151, 9, v136
	v_lshl_add_u32 v151, v139, 7, v151
	v_lshl_add_u32 v151, v138, 4, v151
	v_lshlrev_b32_e32 v152, 11, v138
	v_lshl_add_u32 v152, v139, 7, v152
	v_lshl_add_u32 v152, v136, 2, v152
	v_lshlrev_b32_e32 v153, 6, v136
	v_lshl_add_u32 v153, v138, 4, v153
	v_lshlrev_b32_e32 v154, 4, v138
	v_and_b32_e32 v140, 63, v2
	v_lshlrev_b32_e32 v156, 4, v140
	v_add_u32_e32 v156, 0x8a00, v156
	s_mul_i32 s101, s100, 0xc00
	v_add_u32_e32 v155, s101, v156
	v_lshlrev_b32_e32 v157, 5, v2
	v_lshl_add_u32 v158, v136, 4, v137
	v_lshlrev_b32_e32 v158, 2, v158
	v_add_u32_e32 v158, 16384, v158
	v_lshlrev_b32_e32 v159, 2, v136
	v_lshlrev_b32_e32 v141, 2, v138
	v_add_u32_e32 v142, 0, v141
	v_cmp_le_u32_e32 vcc, v142, v136
	s_nop 1
	v_cndmask_b32_e64 v166, 0, 1.0, vcc
	v_add_u32_e32 v142, 1, v141
	v_cmp_le_u32_e32 vcc, v142, v136
	s_nop 1
	v_cndmask_b32_e64 v167, 0, 1.0, vcc
	v_add_u32_e32 v142, 2, v141
	v_cmp_le_u32_e32 vcc, v142, v136
	s_nop 1
	v_cndmask_b32_e64 v168, 0, 1.0, vcc
	v_add_u32_e32 v142, 3, v141
	v_cmp_le_u32_e32 vcc, v142, v136
	s_nop 1
	v_cndmask_b32_e64 v169, 0, 1.0, vcc
	v_readlane_b32 s101, v244, 27
	s_bfe_u32 s101, s101, 0x20003
	v_add_u32_e32 v142, s13, v137
	s_lshl_b32 s14, s101, 8
	v_lshl_add_u32 v143, v136, 4, s14
	s_movk_i32 s15, 0xc00
	v_mad_u32_u24 v118, v142, s15, v143
	s_add_i32 s14, s14, s12
	v_lshl_add_u32 v143, v136, 1, s14
	v_mad_u32_u24 v119, v142, s15, v143
	v_add_u32_e32 v119, 0x800, v119
	v_add_u32_e32 v142, s13, v136
	s_lshl_b32 s15, s101, 2
	v_lshl_add_u32 v140, v142, 5, s15
	v_add_u32_e32 v142, s13, v141
	v_lshl_add_u32 v57, v142, 11, v143
	v_add_u32_e32 v57, 0x400, v57
	v_add_u32_e32 v58, 0x1000, v57
	v_lshlrev_b32_e32 v59, 6, v136
	v_lshl_add_u32 v59, v138, 4, v59
	v_readlane_b32 s14, v244, 27
	s_lshr_b32 s14, s14, 3
	s_mul_i32 s12, s14, 0x80400
	v_readlane_b32 s14, v247, 3
	v_readlane_b32 s15, v247, 4
	s_add_u32 s14, s14, 0xac40000
	s_addc_u32 s15, s15, 0
	s_add_u32 s14, s14, s12
	s_addc_u32 s15, s15, 0
	v_mov_b32_e32 v12, 0
	v_mov_b32_e32 v13, 0
	v_mov_b32_e32 v14, 0
	v_mov_b32_e32 v15, 0
	v_mov_b32_e32 v16, 0
	v_mov_b32_e32 v17, 0
	v_mov_b32_e32 v18, 0
	v_mov_b32_e32 v19, 0
	s_barrier
	global_load_dwordx4 v[108:111], v118, s[4:5]
	global_load_dwordx4 v[112:115], v118, s[4:5] offset:1024
	global_load_ushort v116, v119, s[4:5]
	global_load_dword v117, v140, s[6:7]
	s_add_u32 s4, s4, 0xc000
	s_addc_u32 s5, s5, 0
	s_add_u32 s6, s6, 0x200
	s_addc_u32 s7, s7, 0
	global_load_dwordx4 v[88:91], v59, s[10:11]
	s_add_u32 s10, s10, 0x400
	s_addc_u32 s11, s11, 0
	global_load_dwordx4 v[92:95], v59, s[14:15]
	s_add_u32 s14, s14, 0x400
	s_addc_u32 s15, s15, 0
	v_mov_b32_e32 v148, v157
	v_mov_b32_e32 v149, v158
	v_mov_b32_e32 v150, v159
	s_waitcnt vmcnt(0)
	v_lshlrev_b32_e32 v120, 16, v108
	v_and_b32_e32 v121, 0xffff0000, v108
	v_lshlrev_b32_e32 v122, 16, v109
	v_and_b32_e32 v123, 0xffff0000, v109
	v_lshlrev_b32_e32 v124, 16, v110
	v_and_b32_e32 v125, 0xffff0000, v110
	v_lshlrev_b32_e32 v126, 16, v111
	v_and_b32_e32 v127, 0xffff0000, v111
	v_lshlrev_b32_e32 v128, 16, v112
	v_and_b32_e32 v129, 0xffff0000, v112
	v_lshlrev_b32_e32 v130, 16, v113
	v_and_b32_e32 v131, 0xffff0000, v113
	v_lshlrev_b32_e32 v132, 16, v114
	v_and_b32_e32 v133, 0xffff0000, v114
	v_lshlrev_b32_e32 v134, 16, v115
	v_and_b32_e32 v135, 0xffff0000, v115
	v_mov_b32_e32 v136, v117
	v_lshlrev_b32_e32 v137, 16, v116
	s_nop 0
	v_add_f32_dpp v136, v136, v136 row_shr:1 row_mask:0xf bank_mask:0xf bound_ctrl:1
	s_nop 1
	v_add_f32_dpp v136, v136, v136 row_shr:2 row_mask:0xf bank_mask:0xf bound_ctrl:1
	s_nop 1
	v_add_f32_dpp v136, v136, v136 row_shr:4 row_mask:0xf bank_mask:0xf bound_ctrl:1
	s_nop 1
	v_add_f32_dpp v136, v136, v136 row_shr:8 row_mask:0xf bank_mask:0xf bound_ctrl:1
	s_nop 0
	v_max_f32_e32 v136, 0xc2a00000, v136
	v_mul_f32_e32 v136, 0x3fb8aa3b, v136
	v_exp_f32_e32 v138, v136
	v_exp_f32_e64 v139, -v136
	s_nop 0
	v_mul_f32_e32 v136, 0x3db504f3, v138
	ds_write_b128 v148, v[120:123]
	ds_write_b128 v148, v[124:127] offset:16
	ds_write_b128 v148, v[128:131] offset:8192
	ds_write_b128 v148, v[132:135] offset:8208
	ds_write_b32 v149, v137
	ds_write_b32 v150, v139 offset:17408
	ds_write_b32 v150, v138 offset:17536
	ds_write_b32 v150, v136 offset:17472
	global_load_dwordx4 v[108:111], v118, s[4:5]
	global_load_dwordx4 v[112:115], v118, s[4:5] offset:1024
	global_load_ushort v116, v119, s[4:5]
	global_load_dword v117, v140, s[6:7]
	s_add_u32 s4, s4, 0xc000
	s_addc_u32 s5, s5, 0
	s_add_u32 s6, s6, 0x200
	s_addc_u32 s7, s7, 0
	s_mov_b32 s0, 0
	s_mov_b32 s1, 0
	s_sub_u32 s8, s8, 0x8000
	s_subb_u32 s9, s9, 0
	s_waitcnt vmcnt(0) lgkmcnt(0)
	s_barrier
; __device__ __forceinline__ void gdn_item(const Params& p, int item, float* sm) {
;     ...
;   for (int ch = 0; ch < NCH; ch++) {
;     const int bi = ch & 1;
;     const int t0 = PADR + ch * TC;
;     if (ch + 1 < NCH) GDN_LOAD(t0 + TC)
;     {
;       const float* bq = sm + bi * BUF;
;       const float* bk = bq + TC * 128;
;       const float* bv = bq + 2 * TC * 128;
;       const float* bg = bv + TC * 16;
;       float* bo = sm + bi * BUF + 2 * TC * 128 + TC * 16 + 2 * TC;
;       float oreg[TC];
; #pragma unroll
;       for (int t = 0; t < TC; t++) {
;         const float4 k0 = *(const float4*)(bk + t * 128 + sub * 4);
;         const float4 k1 = *(const float4*)(bk + t * 128 + 64 + sub * 4);
;         const float4 q0 = *(const float4*)(bq + t * 128 + sub * 4);
;         const float4 q1 = *(const float4*)(bq + t * 128 + 64 + sub * 4);
;         const float v = bv[t * 16 + cw];
;         const float g = bg[t], be = bg[TC + t];
;         const float qk = bo[TC * 16 + t];
;         float pa = k0.x * S[0] + k0.y * S[1];
;         float pb2 = k0.z * S[2] + k0.w * S[3];
;         float qa = q0.x * S[0] + q0.y * S[1];
;         float qb2 = q0.z * S[2] + q0.w * S[3];
;         pa += k1.x * S[4] + k1.y * S[5];
;         pb2 += k1.z * S[6] + k1.w * S[7];
;         qa += q1.x * S[4] + q1.y * S[5];
;         qb2 += q1.z * S[6] + q1.w * S[7];
;         const float ks = dpp_sum16(pa + pb2);
;         const float qs = dpp_sum16(qa + qb2);
;         const float coef = be * (v - g * ks);
;         const float oo = g * qs + coef * qk;
;         S[0] = g * S[0] + coef * k0.x; S[1] = g * S[1] + coef * k0.y; S[2] = g * S[2] + coef * k0.z; S[3] = g * S[3] + coef * k0.w;
;         S[4] = g * S[4] + coef * k1.x; S[5] = g * S[5] + coef * k1.y; S[6] = g * S[6] + coef * k1.z; S[7] = g * S[7] + coef * k1.w;
;         oreg[t] = oo * 0.08838834764831845f;
;       }
;       if (sub == 0) {
; #pragma unroll
;         for (int t = 0; t < TC; t++) bo[t * 16 + cw] = oreg[t];
;       }
;     }
;     if (ch + 1 < NCH) GDN_STORE(bi ^ 1)
.Lgd_chunk:
	v_add_u32_e32 v141, s1, v151
	v_add_u32_e32 v142, s1, v152
	v_add_u32_e32 v143, s1, v153
	v_add_u32_e32 v144, s1, v154
	v_mov_b32_e32 v145, s1
	s_xor_b32 s2, s1, 0x4500
	s_and_b32 s12, s0, 1
	s_mul_i32 s12, s12, 0x3000
	v_add_u32_e32 v146, s12, v155
	v_add_u32_e32 v147, s12, v156
	ds_read_b128 v[20:23], v141 offset:8192
	ds_read_b128 v[28:31], v141 offset:0
	ds_read_b128 v[24:27], v141 offset:8256
	ds_read_b128 v[32:35], v141 offset:64
	v_add_u32_e32 v148, s2, v157
	v_add_u32_e32 v149, s2, v158
	v_add_u32_e32 v150, s2, v159
	s_waitcnt lgkmcnt(0)
	v_mfma_f32_16x16x4_f32 v[60:63], v20, v12, 0
	ds_read_b32 v36, v142 offset:8192
	v_mfma_f32_16x16x4_f32 v[64:67], v28, v12, 0
	ds_read_b32 v37, v142 offset:8704
	v_mfma_f32_16x16x4_f32 v[60:63], v21, v13, v[60:63]
	ds_read_b32 v38, v142 offset:9216
	v_mfma_f32_16x16x4_f32 v[64:67], v29, v13, v[64:67]
	ds_read_b32 v39, v142 offset:9728
	s_waitcnt vmcnt(2)
	v_lshlrev_b32_e32 v120, 16, v108
	v_and_b32_e32 v121, 0xffff0000, v108
	v_lshlrev_b32_e32 v122, 16, v109
	v_mfma_f32_16x16x4_f32 v[60:63], v22, v14, v[60:63]
	ds_read_b32 v40, v142 offset:8256
	v_and_b32_e32 v123, 0xffff0000, v109
	v_lshlrev_b32_e32 v124, 16, v110
	v_and_b32_e32 v125, 0xffff0000, v110
	v_mfma_f32_16x16x4_f32 v[64:67], v30, v14, v[64:67]
	ds_read_b32 v41, v142 offset:8768
	v_lshlrev_b32_e32 v126, 16, v111
	v_and_b32_e32 v127, 0xffff0000, v111
	v_lshlrev_b32_e32 v128, 16, v112
	v_and_b32_e32 v129, 0xffff0000, v112
	v_mfma_f32_16x16x4_f32 v[60:63], v23, v15, v[60:63]
	ds_read_b32 v42, v142 offset:9280
	v_lshlrev_b32_e32 v130, 16, v113
	v_and_b32_e32 v131, 0xffff0000, v113
	v_lshlrev_b32_e32 v132, 16, v114
	v_mfma_f32_16x16x4_f32 v[64:67], v31, v15, v[64:67]
	ds_read_b32 v43, v142 offset:9792
	v_and_b32_e32 v133, 0xffff0000, v114
	v_lshlrev_b32_e32 v134, 16, v115
	v_and_b32_e32 v135, 0xffff0000, v115
	v_mov_b32_e32 v136, v117
	v_mfma_f32_16x16x4_f32 v[60:63], v24, v16, v[60:63]
	ds_read_b128 v[44:47], v143 offset:16384
	v_lshlrev_b32_e32 v137, 16, v116
	s_nop 0
	v_add_f32_dpp v136, v136, v136 row_shr:1 row_mask:0xf bank_mask:0xf bound_ctrl:1
	v_mfma_f32_16x16x4_f32 v[64:67], v32, v16, v[64:67]
	ds_read_b128 v[48:51], v144 offset:17408
	s_nop 1
	v_add_f32_dpp v136, v136, v136 row_shr:2 row_mask:0xf bank_mask:0xf bound_ctrl:1
	s_nop 1
	v_add_f32_dpp v136, v136, v136 row_shr:4 row_mask:0xf bank_mask:0xf bound_ctrl:1
	v_mfma_f32_16x16x4_f32 v[60:63], v25, v17, v[60:63]
	ds_read_b128 v[52:55], v144 offset:17472
	s_nop 1
	v_add_f32_dpp v136, v136, v136 row_shr:8 row_mask:0xf bank_mask:0xf bound_ctrl:1
	s_nop 0
	v_mfma_f32_16x16x4_f32 v[64:67], v33, v17, v[64:67]
	ds_read_b32 v56, v145 offset:17596
	v_max_f32_e32 v136, 0xc2a00000, v136
	v_mul_f32_e32 v136, 0x3fb8aa3b, v136
	v_exp_f32_e32 v138, v136
	v_exp_f32_e64 v139, -v136
	v_mfma_f32_16x16x4_f32 v[60:63], v26, v18, v[60:63]
	s_nop 0
	v_mul_f32_e32 v136, 0x3db504f3, v138
	ds_write_b128 v148, v[120:123]
	v_mfma_f32_16x16x4_f32 v[64:67], v34, v18, v[64:67]
	ds_write_b128 v148, v[124:127] offset:16
	ds_write_b128 v148, v[128:131] offset:8192
	ds_write_b128 v148, v[132:135] offset:8208
	ds_write_b32 v149, v137
	v_mfma_f32_16x16x4_f32 v[60:63], v27, v19, v[60:63]
	ds_write_b32 v150, v139 offset:17408
	ds_write_b32 v150, v138 offset:17536
	ds_write_b32 v150, v136 offset:17472
	v_mfma_f32_16x16x4_f32 v[64:67], v35, v19, v[64:67]
	global_load_dwordx4 v[108:111], v118, s[4:5]
	global_load_dwordx4 v[112:115], v118, s[4:5] offset:1024
	global_load_ushort v116, v119, s[4:5]
	global_load_dword v117, v140, s[6:7]
	s_cmp_lt_u32 s0, 0x1fe
	s_cselect_b32 s12, 0xc000, 0
	s_cselect_b32 s101, 0x200, 0
	s_add_u32 s4, s4, s12
	s_addc_u32 s5, s5, 0
	s_add_u32 s6, s6, s101
	s_addc_u32 s7, s7, 0
	s_nop 3
	ds_write_b128 v146, v[60:63]
	ds_write_b128 v146, v[64:67] offset:1024
	s_waitcnt lgkmcnt(0)
	s_barrier
	ds_read_b128 v[72:75], v147 offset:0
	ds_read_b128 v[76:79], v147 offset:3072
	ds_read_b128 v[80:83], v147 offset:6144
	ds_read_b128 v[84:87], v147 offset:9216
	s_waitcnt vmcnt(4) lgkmcnt(0)
	s_add_i32 s12, s0, 3
	s_and_b32 s12, s12, 3
	s_cmp_eq_u32 s12, s100
	s_cbranch_scc0 .Lgd_nopend
	s_cmp_eq_u32 s0, 0
	s_cbranch_scc1 .Lgd_nopend
	global_store_short v57, v104, s[8:9]
	global_store_short v57, v105, s[8:9] offset:2048
	global_store_short v58, v106, s[8:9]
	global_store_short v58, v107, s[8:9] offset:2048
; __device__ __forceinline__ void gdn_item(const Params& p, int item, float* sm) {
;     ...
;         const float ks = dpp_sum16(pa + pb2);
;         const float qs = dpp_sum16(qa + qb2);
;         const float coef = be * (v - g * ks);
;         const float oo = g * qs + coef * qk;
;         S[0] = g * S[0] + coef * k0.x; S[1] = g * S[1] + coef * k0.y; S[2] = g * S[2] + coef * k0.z; S[3] = g * S[3] + coef * k0.w;
;         S[4] = g * S[4] + coef * k1.x; S[5] = g * S[5] + coef * k1.y; S[6] = g * S[6] + coef * k1.z; S[7] = g * S[7] + coef * k1.w;
;         oreg[t] = oo * 0.08838834764831845f;
;       }
;       if (sub == 0) {
; #pragma unroll
;         for (int t = 0; t < TC; t++) bo[t * 16 + cw] = oreg[t];
;       }
;     }
;     if (ch + 1 < NCH) GDN_STORE(bi ^ 1)
;     __syncthreads();
;     {
;       const float ov = sm[bi * BUF + 2 * TC * 128 + TC * 16 + 2 * TC + ltt * 16 + lseg];
;       O[(rowb + t0 + ltt) * D + 512 + h * 128 + c0 + lseg] = f2bf(ov);
;     }
.Lgd_nopend:
	v_add_f32_e32 v72, v72, v76
	v_add_f32_e32 v80, v80, v84
	v_add_f32_e32 v73, v73, v77
	v_add_f32_e32 v81, v81, v85
	v_add_f32_e32 v74, v74, v78
	v_add_f32_e32 v82, v82, v86
	v_add_f32_e32 v75, v75, v79
	v_add_f32_e32 v83, v83, v87
	v_add_f32_e32 v72, v72, v80
	v_add_f32_e32 v73, v73, v81
	v_add_f32_e32 v74, v74, v82
	v_add_f32_e32 v75, v75, v83
	v_fma_f32 v96, v44, v48, -v72
	v_fma_f32 v97, v45, v49, -v73
	v_fma_f32 v98, v46, v50, -v74
	v_fma_f32 v99, v47, v51, -v75
	s_nop 1
	v_mfma_f32_16x16x4_f32 v[100:103], v88, v96, 0
	v_mfma_f32_16x16x4_f32 v[100:103], v89, v97, v[100:103]
	v_mfma_f32_16x16x4_f32 v[100:103], v90, v98, v[100:103]
	v_mfma_f32_16x16x4_f32 v[100:103], v91, v99, v[100:103]
	global_load_dwordx4 v[88:91], v59, s[10:11]
	s_cmp_lt_u32 s0, 0x1ff
	s_cselect_b32 s12, 0x400, 0
	s_add_u32 s10, s10, s12
	s_addc_u32 s11, s11, 0
	s_and_b32 s12, s0, 3
	s_cmp_eq_u32 s12, s100
	s_cbranch_scc0 .Lgd_upd
	ds_read_b128 v[72:75], v147 offset:1024
	ds_read_b128 v[76:79], v147 offset:4096
	ds_read_b128 v[80:83], v147 offset:7168
	ds_read_b128 v[84:87], v147 offset:10240
	s_waitcnt lgkmcnt(0)
	v_add_f32_e32 v72, v72, v76
	v_add_f32_e32 v80, v80, v84
	v_add_f32_e32 v73, v73, v77
	v_add_f32_e32 v81, v81, v85
	v_add_f32_e32 v74, v74, v78
	v_add_f32_e32 v82, v82, v86
	v_add_f32_e32 v75, v75, v79
	v_add_f32_e32 v83, v83, v87
	v_add_f32_e32 v104, v72, v80
	v_add_f32_e32 v105, v73, v81
	v_add_f32_e32 v106, v74, v82
	v_add_f32_e32 v107, v75, v83
	s_nop 7
	s_nop 1
	v_mfma_f32_16x16x4_f32 v[104:107], v92, v100, v[104:107]
	v_mfma_f32_16x16x4_f32 v[104:107], v93, v101, v[104:107]
	v_mfma_f32_16x16x4_f32 v[104:107], v94, v102, v[104:107]
	v_mfma_f32_16x16x4_f32 v[104:107], v95, v103, v[104:107]
.Lgd_upd:
	global_load_dwordx4 v[92:95], v59, s[14:15]
	s_cmp_lt_u32 s0, 0x1ff
	s_cselect_b32 s101, 0x400, 0
	s_add_u32 s14, s14, s101
	s_addc_u32 s15, s15, 0
	s_nop 5
	v_mfma_f32_16x16x4_f32 v[12:15], v36, v100, v[12:15]
	v_mfma_f32_16x16x4_f32 v[16:19], v40, v100, v[16:19]
	v_mfma_f32_16x16x4_f32 v[12:15], v37, v101, v[12:15]
	v_mfma_f32_16x16x4_f32 v[16:19], v41, v101, v[16:19]
	v_mfma_f32_16x16x4_f32 v[12:15], v38, v102, v[12:15]
	v_mfma_f32_16x16x4_f32 v[16:19], v42, v102, v[16:19]
	v_mfma_f32_16x16x4_f32 v[12:15], v39, v103, v[12:15]
	v_mfma_f32_16x16x4_f32 v[16:19], v43, v103, v[16:19]
	s_cmp_eq_u32 s12, s100
	s_cbranch_scc0 .Lgd_noout
	s_nop 7
	s_nop 3
	v_mul_f32_e32 v104, v104, v52
	v_mul_f32_e32 v105, v105, v53
	v_mul_f32_e32 v106, v106, v54
	v_mul_f32_e32 v107, v107, v55
	v_cvt_pk_bf16_f32 v104, v104, v104
	v_cvt_pk_bf16_f32 v105, v105, v105
	v_cvt_pk_bf16_f32 v106, v106, v106
	v_cvt_pk_bf16_f32 v107, v107, v107
.Lgd_noout:
	s_add_u32 s8, s8, 0x8000
	s_addc_u32 s9, s9, 0
	s_nop 6
	v_mul_f32_e32 v12, v12, v56
	v_mul_f32_e32 v13, v13, v56
	v_mul_f32_e32 v14, v14, v56
	v_mul_f32_e32 v15, v15, v56
	v_mul_f32_e32 v16, v16, v56
	v_mul_f32_e32 v17, v17, v56
	v_mul_f32_e32 v18, v18, v56
	v_mul_f32_e32 v19, v19, v56
	s_mov_b32 s1, s2
	s_add_i32 s0, s0, 1
	s_cmp_lg_u32 s0, 513
	s_cbranch_scc1 .Lgd_chunk
	s_cmp_eq_u32 s100, 0
	s_cbranch_scc0 .Lgd_nopend2
	global_store_short v57, v104, s[8:9]
	global_store_short v57, v105, s[8:9] offset:2048
	global_store_short v58, v106, s[8:9]
	global_store_short v58, v107, s[8:9] offset:2048
